# M2 table quantisation: base pointers read once instead of per row, next row requested one row ahead (prologue de-serialisation)
# speedup vs baseline: 1.0069x; 1.0069x over previous
; __device__ __forceinline__ int vblk() { return (int)blockIdx.x * 2 + half_id(); }
; __device__ __forceinline__ int vgrid() { return (int)gridDim.x * 2; }
; __device__ void phaseM2(const Params& p, char* lds) {
;     ...
;         for (int row = vblk() * 4 + wave; row < 32768; row += vgrid() * 4) {
;             const bool isv = row >= 16384;
;             const float* srcp = (isv ? p.peer_v : p.peer_u) + (size_t)(row & 16383) * DM + lane * 16;
;             f32x4 a[4];
;             float mx = 0.f;
; #pragma unroll
;             for (int i = 0; i < 4; i++) {
;                 a[i] = *(const f32x4*)(srcp + i * 4);
.LBB0_790:
	v_readfirstlane_b32 s0, v158
	s_lshr_b32 s1, s0, 6
	v_mov_b32_e32 v1, v158
	s_and_b32 s1, s1, 0x3fffffc
	v_readlane_b32 s28, v222, 5
	s_add_i32 s1, s1, s28
	v_bfe_u32 v0, v1, 6, 2
	v_or_b32_e32 v16, s1, v0
	s_mov_b32 s1, 0x8000
	v_cmp_gt_i32_e32 vcc, s1, v16
	s_and_saveexec_b64 s[10:11], vcc
	s_cbranch_execz .LBB0_801
	v_and_b32_e32 v3, 64, v159
	v_add_u32_e32 v3, 64, v3
	v_xor_b32_e32 v4, 32, v159
	v_cmp_lt_i32_e32 vcc, v4, v3
	v_and_b32_e32 v1, 63, v1
	v_mov_b32_e32 v19, 0
	v_cndmask_b32_e32 v4, v159, v4, vcc
	v_lshlrev_b32_e32 v26, 2, v4
	v_xor_b32_e32 v4, 16, v159
	v_cmp_lt_i32_e32 vcc, v4, v3
	v_lshlrev_b32_e32 v18, 3, v1
	s_mov_b64 s[2:3], 0xac00000
	v_cndmask_b32_e32 v4, v159, v4, vcc
	v_lshlrev_b32_e32 v27, 2, v4
	v_xor_b32_e32 v4, 8, v159
	v_cmp_lt_i32_e32 vcc, v4, v3
	v_ashrrev_i32_e32 v17, 31, v16
	s_add_u32 s12, s6, 0xbc00000
	v_cndmask_b32_e32 v4, v159, v4, vcc
	v_lshlrev_b32_e32 v28, 2, v4
	v_xor_b32_e32 v4, 4, v159
	v_cmp_lt_i32_e32 vcc, v4, v3
	s_addc_u32 s13, s7, 0
	s_lshl_b32 s14, s72, 3
	v_cndmask_b32_e32 v4, v159, v4, vcc
	v_lshlrev_b32_e32 v29, 2, v4
	v_xor_b32_e32 v4, 2, v159
	v_cmp_lt_i32_e32 vcc, v4, v3
	v_readlane_b32 s1, v222, 0
	s_lshr_b32 s0, s0, 5
	v_cndmask_b32_e32 v4, v159, v4, vcc
	v_lshlrev_b32_e32 v30, 2, v4
	v_xor_b32_e32 v4, 1, v159
	v_cmp_lt_i32_e32 vcc, v4, v3
	v_lshlrev_b32_e32 v2, 4, v1
	s_ashr_i32 s15, s14, 31
	v_cndmask_b32_e32 v3, v159, v4, vcc
	v_lshl_add_u64 v[4:5], s[6:7], 0, v[18:19]
	v_lshl_add_u64 v[20:21], v[4:5], 0, s[2:3]
	v_lshlrev_b64 v[4:5], 9, v[16:17]
	v_or_b32_e32 v4, v4, v18
	v_lshl_add_u64 v[4:5], s[6:7], 0, v[4:5]
	s_mov_b64 s[2:3], 0x9c00000
	s_lshl_b32 s1, s1, 4
	s_and_b32 s0, s0, 0x7fffff8
	v_lshlrev_b32_e32 v31, 2, v3
	v_cmp_eq_u32_e64 s[4:5], 0, v1
	v_lshl_add_u64 v[22:23], v[4:5], 0, s[2:3]
	s_lshl_b64 s[16:17], s[14:15], 9
	v_lshlrev_b32_e32 v17, 1, v0
	s_add_i32 s0, s1, s0
	s_lshl_b32 s1, s72, 4
	v_lshlrev_b32_e32 v32, 10, v16
	s_lshl_b32 s2, s72, 13
	s_mov_b64 s[18:19], 0
	s_movk_i32 s3, 0x4000
	s_movk_i32 s15, 0x3fff
	v_mov_b32_e32 v33, 0xc0
	v_mov_b32_e32 v34, 0xc8
	v_lshlrev_b32_e32 v24, 2, v2
	v_mov_b32_e32 v25, v19
	s_mov_b32 s22, 0xf800000
	v_mov_b32_e32 v35, 0x260
	s_mov_b32 s23, 0x40e00000
	s_mov_b32 s24, 0x40c00000
	s_movk_i32 s25, 0x7fff
	s_load_dwordx4 s[52:55], s[8:9], 0xc0
	s_waitcnt lgkmcnt(0)
	v_mov_b32_e32 v62, s52
	v_mov_b32_e32 v63, s53
	v_mov_b32_e32 v64, s54
	v_mov_b32_e32 v65, s55
	v_mov_b32_e32 v67, 0
	v_mov_b32_e32 v66, v32
	v_and_b32_e32 v66, 0xfffc00, v66
	v_lshlrev_b32_e32 v66, 2, v66
	v_cmp_lt_i32_e32 vcc, s15, v16
	s_nop 1
	v_cndmask_b32_e32 v68, v62, v64, vcc
	v_cndmask_b32_e32 v69, v63, v65, vcc
	v_lshl_add_u64 v[68:69], v[68:69], 0, v[66:67]
	v_lshl_add_u64 v[68:69], v[68:69], 0, v[24:25]
	global_load_dwordx4 v[58:61], v[68:69], off
	global_load_dwordx4 v[54:57], v[68:69], off offset:16
	global_load_dwordx4 v[50:53], v[68:69], off offset:32
	global_load_dwordx4 v[46:49], v[68:69], off offset:48
	s_waitcnt vmcnt(0)
	s_branch .Lq_body

; __device__ __forceinline__ int vblk() { return (int)blockIdx.x * 2 + half_id(); }
; __device__ __forceinline__ int vgrid() { return (int)gridDim.x * 2; }
; __device__ void phaseM2(const Params& p, char* lds) {
;     ...
;         for (int row = vblk() * 4 + wave; row < 32768; row += vgrid() * 4) {
;             const bool isv = row >= 16384;
;             const float* srcp = (isv ? p.peer_v : p.peer_u) + (size_t)(row & 16383) * DM + lane * 16;
;             f32x4 a[4];
;             float mx = 0.f;
; #pragma unroll
;             for (int i = 0; i < 4; i++) {
;                 a[i] = *(const f32x4*)(srcp + i * 4);
.LBB0_794:
	s_waitcnt vmcnt(2)
.Lq_body:
	v_mov_b32_e32 v0, v46
	v_mov_b32_e32 v1, v47
	v_mov_b32_e32 v2, v48
	v_mov_b32_e32 v3, v49
	v_mov_b32_e32 v4, v50
	v_mov_b32_e32 v5, v51
	v_mov_b32_e32 v6, v52
	v_mov_b32_e32 v7, v53
	v_mov_b32_e32 v8, v54
	v_mov_b32_e32 v9, v55
	v_mov_b32_e32 v10, v56
	v_mov_b32_e32 v11, v57
	v_mov_b32_e32 v12, v58
	v_mov_b32_e32 v13, v59
	v_mov_b32_e32 v14, v60
	v_mov_b32_e32 v15, v61
	v_add_u32_e32 v70, s14, v16
	v_cmp_ge_i32_e32 vcc, s25, v70
	s_and_saveexec_b64 s[26:27], vcc
	s_cbranch_execz .Lq_nopf
	v_add_u32_e32 v66, s2, v32
	v_and_b32_e32 v66, 0xfffc00, v66
	v_lshlrev_b32_e32 v66, 2, v66
	v_cmp_lt_i32_e32 vcc, s15, v70
	s_nop 1
	v_cndmask_b32_e32 v68, v62, v64, vcc
	v_cndmask_b32_e32 v69, v63, v65, vcc
	v_lshl_add_u64 v[68:69], v[68:69], 0, v[66:67]
	v_lshl_add_u64 v[68:69], v[68:69], 0, v[24:25]
	global_load_dwordx4 v[58:61], v[68:69], off
	global_load_dwordx4 v[54:57], v[68:69], off offset:16
	global_load_dwordx4 v[50:53], v[68:69], off offset:32
	global_load_dwordx4 v[46:49], v[68:69], off offset:48
; __device__ void phaseM2(const Params& p, char* lds) {
;     ...
;             const float* srcp = (isv ? p.peer_v : p.peer_u) + (size_t)(row & 16383) * DM + lane * 16;
;             f32x4 a[4];
;             float mx = 0.f;
; #pragma unroll
;             for (int i = 0; i < 4; i++) {
;                 a[i] = *(const f32x4*)(srcp + i * 4);
;                 mx = fmaxf(mx, fmaxf(fmaxf(fabsf(a[i][0]), fabsf(a[i][1])), fmaxf(fabsf(a[i][2]), fabsf(a[i][3]))));
;             }
;             mx = wave_max(mx);
;             if (isv) {
;                 const float inv = mx > 0.f ? 6.f / mx : 0.f;
;                 unsigned w[2];
; #pragma unroll
;                 for (int i = 0; i < 2; i++) {
;                     unsigned t = 0u;
;                     t = __builtin_amdgcn_cvt_scalef32_pk_fp4_f32(t, a[2 * i][0] * inv, a[2 * i][1] * inv, 1.0f, 0);
;                     t = __builtin_amdgcn_cvt_scalef32_pk_fp4_f32(t, a[2 * i][2] * inv, a[2 * i][3] * inv, 1.0f, 1);
;                     t = __builtin_amdgcn_cvt_scalef32_pk_fp4_f32(t, a[2 * i + 1][0] * inv, a[2 * i + 1][1] * inv, 1.0f, 2);
;                     t = __builtin_amdgcn_cvt_scalef32_pk_fp4_f32(t, a[2 * i + 1][2] * inv, a[2 * i + 1][3] * inv, 1.0f, 3);
;                     w[i] = t;
;                 }
;                 *(u32x2*)(tq + 16777216 + (size_t)(row - 16384) * 512 + lane * 8) = (u32x2){w[0], w[1]};
;                 if (lane == 0) tsc[2 * (row - 16384) + 1] = mx * (1.f / 6.f);
;             } else {
;                 float ssq = 0.f;
; #pragma unroll
;                 for (int i = 0; i < 4; i++) ssq += a[i][0] * a[i][0] + a[i][1] * a[i][1] + a[i][2] * a[i][2] + a[i][3] * a[i][3];
;                 ssq = wave_sum(ssq);
;                 mx = fminf(mx, 2.4f * sqrtf(ssq * (1.f / 1024.f)));
;                 const float inv = mx > 0.f ? 7.f / mx : 0.f;
;                 unsigned w2[2] = {0u, 0u};
; #pragma unroll
;                 for (int i = 0; i < 4; i++)
; #pragma unroll
;                     for (int j = 0; j < 4; j++) {
;                         const int e = i * 4 + j;
;                         int qi = (int)rintf(a[i][j] * inv);
;                         qi = qi > 7 ? 7 : (qi < -7 ? -7 : qi);
;                         w2[e >> 3] |= (unsigned)(qi & 15) << ((e & 7) * 4);
;                     }
;                 *(u32x2*)(tq + (size_t)row * 512 + lane * 8) = (u32x2){w2[0], w2[1]};
.Lq_nopf:
	s_or_b64 exec, exec, s[26:27]
	v_cmp_gt_i32_e32 vcc, s3, v16
	v_max_f32_e64 v18, |v15|, |v15|
	v_max_f32_e64 v36, |v14|, |v14|
	v_max_f32_e64 v37, |v11|, |v11|
	v_max_f32_e64 v38, |v10|, |v10|
	v_max_f32_e64 v39, |v7|, |v7|
	v_max_f32_e64 v40, |v6|, |v6|
	v_max_f32_e64 v41, |v3|, |v3|
	v_max_f32_e64 v42, |v2|, |v2|
	v_max_f32_e32 v18, v36, v18
	v_max_f32_e32 v36, v38, v37
	v_max_f32_e32 v37, v40, v39
	v_max_f32_e32 v38, v42, v41
	v_max3_f32 v18, |v12|, |v13|, v18
	v_max3_f32 v36, |v8|, |v9|, v36
	v_max3_f32 v37, |v4|, |v5|, v37
	v_max3_f32 v18, v18, 0, v36
	v_max3_f32 v36, |v0|, |v1|, v38
	v_max3_f32 v18, v18, v37, v36
	s_nop 1
	v_max_f32_dpp v18, v18, v18 row_ror:8 row_mask:0xf bank_mask:0xf
	s_nop 1
	v_max_f32_dpp v18, v18, v18 row_ror:4 row_mask:0xf bank_mask:0xf
	s_nop 1
	v_max_f32_dpp v18, v18, v18 row_ror:2 row_mask:0xf bank_mask:0xf
	s_nop 1
	v_max_f32_dpp v18, v18, v18 row_ror:1 row_mask:0xf bank_mask:0xf
	v_mov_b32_e32 v36, v18
	s_nop 1
	v_permlane16_swap_b32_e32 v18, v36
	v_max_f32_e32 v18, v18, v36
	v_mov_b32_e32 v36, v18
	s_nop 1
	v_permlane32_swap_b32_e32 v18, v36
	v_max_f32_e32 v36, v18, v36
	s_and_saveexec_b64 s[6:7], vcc
	s_xor_b64 s[20:21], exec, s[6:7]
	s_cbranch_execz .LBB0_798
	v_mul_f32_e32 v18, v13, v13
	v_mul_f32_e32 v37, v9, v9
	v_mov_b32_e32 v40, v5
	v_mov_b32_e32 v41, v1
	v_fmac_f32_e32 v18, v12, v12
	v_fmac_f32_e32 v37, v8, v8
	v_mov_b32_e32 v38, v4
	v_mov_b32_e32 v39, v0
	v_pk_mul_f32 v[40:41], v[40:41], v[40:41]
	v_fmac_f32_e32 v18, v14, v14
	v_fmac_f32_e32 v37, v10, v10
	v_mov_b32_e32 v42, v6
	v_mov_b32_e32 v43, v2
	v_pk_fma_f32 v[38:39], v[38:39], v[38:39], v[40:41]
	v_fmac_f32_e32 v18, v15, v15
	v_fmac_f32_e32 v37, v11, v11
	v_mov_b32_e32 v44, v7
	v_mov_b32_e32 v45, v3
	v_pk_fma_f32 v[38:39], v[42:43], v[42:43], v[38:39]
	v_add_f32_e32 v18, v18, v37
	v_pk_fma_f32 v[38:39], v[44:45], v[44:45], v[38:39]
	v_max_f32_e32 v36, v36, v36
	v_add_f32_e32 v18, v18, v38
	v_add_f32_e32 v18, v18, v39
	s_nop 1
	v_add_f32_dpp v18, v18, v18 row_ror:8 row_mask:0xf bank_mask:0xf
	s_nop 1
	v_add_f32_dpp v18, v18, v18 row_ror:4 row_mask:0xf bank_mask:0xf
	s_nop 1
	v_add_f32_dpp v18, v18, v18 row_ror:2 row_mask:0xf bank_mask:0xf
	s_nop 1
	v_add_f32_dpp v18, v18, v18 row_ror:1 row_mask:0xf bank_mask:0xf
	v_mov_b32_e32 v37, v18
	s_nop 1
	v_permlane16_swap_b32_e32 v18, v37
	v_add_f32_e32 v18, v18, v37
	v_mov_b32_e32 v37, v18
	s_nop 1
	v_permlane32_swap_b32_e32 v18, v37
	v_add_f32_e32 v18, v18, v37
	v_mul_f32_e32 v18, 0x3a800000, v18
	v_mul_f32_e32 v37, 0x4f800000, v18
	v_cmp_gt_f32_e32 vcc, s22, v18
	s_nop 1
	v_cndmask_b32_e32 v18, v18, v37, vcc
	v_sqrt_f32_e32 v37, v18
	s_nop 0
	v_add_u32_e32 v38, -1, v37
	v_add_u32_e32 v39, 1, v37
	v_fma_f32 v40, -v38, v37, v18
	v_fma_f32 v41, -v39, v37, v18
	v_cmp_ge_f32_e64 s[6:7], 0, v40
	s_nop 1
	v_cndmask_b32_e64 v37, v37, v38, s[6:7]
	v_cmp_lt_f32_e64 s[6:7], 0, v41
	s_nop 1
	v_cndmask_b32_e64 v37, v37, v39, s[6:7]
	v_mul_f32_e32 v38, 0x37800000, v37
	v_cndmask_b32_e32 v37, v37, v38, vcc
	v_cmp_class_f32_e32 vcc, v18, v35
	s_nop 1
	v_cndmask_b32_e32 v18, v37, v18, vcc
	v_mul_f32_e32 v18, 0x4019999a, v18
	v_min_f32_e32 v18, v36, v18
	v_div_scale_f32 v36, s[6:7], v18, v18, s23
	v_rcp_f32_e32 v37, v36
	v_div_scale_f32 v38, vcc, s23, v18, s23
	v_fma_f32 v39, -v36, v37, 1.0
	v_fmac_f32_e32 v37, v39, v37
	v_mul_f32_e32 v39, v38, v37
	v_fma_f32 v40, -v36, v39, v38
	v_fmac_f32_e32 v39, v40, v37
	v_fma_f32 v36, -v36, v39, v38
	v_div_fmas_f32 v36, v36, v37, v39
	v_div_fixup_f32 v36, v36, v18, s23
	v_cmp_lt_f32_e32 vcc, 0, v18
	s_nop 1
	v_cndmask_b32_e32 v36, 0, v36, vcc
	v_mul_f32_e32 v12, v12, v36
	v_mul_f32_e32 v13, v13, v36
	v_mul_f32_e32 v14, v14, v36
	v_rndne_f32_e32 v12, v12
	v_rndne_f32_e32 v13, v13
	v_rndne_f32_e32 v14, v14
	v_mul_f32_e32 v15, v15, v36
	v_mul_f32_e32 v8, v8, v36
	v_mul_f32_e32 v11, v11, v36
	v_cvt_i32_f32_e32 v12, v12
	v_cvt_i32_f32_e32 v13, v13
	v_cvt_i32_f32_e32 v14, v14
	v_rndne_f32_e32 v15, v15
	v_rndne_f32_e32 v8, v8
	v_rndne_f32_e32 v11, v11
	v_cvt_i32_f32_e32 v15, v15
	v_cvt_i32_f32_e32 v8, v8
	v_cvt_i32_f32_e32 v11, v11
	v_med3_i32 v12, v12, -7, 7
	v_med3_i32 v13, v13, -7, 7
	v_med3_i32 v14, v14, -7, 7
	v_and_b32_e32 v12, 15, v12
	v_lshlrev_b32_e32 v13, 4, v13
	v_lshlrev_b32_e32 v14, 8, v14
	v_med3_i32 v15, v15, -7, 7
	v_mul_f32_e32 v9, v9, v36
	v_med3_i32 v8, v8, -7, 7
	v_mul_f32_e32 v10, v10, v36
	v_med3_i32 v11, v11, -7, 7
	v_and_b32_e32 v13, 0xf0, v13
	v_and_b32_e32 v14, 0xf00, v14
	v_lshlrev_b32_e32 v15, 12, v15
	v_rndne_f32_e32 v9, v9
	v_lshlrev_b32_e32 v8, 16, v8
	v_rndne_f32_e32 v10, v10
	v_lshl_or_b32 v11, v11, 28, v12
	v_mul_f32_e32 v4, v4, v36
	v_and_b32_e32 v15, 0xf000, v15
	v_cvt_i32_f32_e32 v9, v9
	v_and_b32_e32 v8, 0xf0000, v8
	v_cvt_i32_f32_e32 v10, v10
	v_or3_b32 v11, v11, v13, v14
	v_rndne_f32_e32 v4, v4
	v_or3_b32 v8, v11, v15, v8
	v_cvt_i32_f32_e32 v11, v4
	v_mul_f32_e32 v4, v5, v36
	v_mul_f32_e32 v6, v6, v36
	v_rndne_f32_e32 v4, v4
	v_rndne_f32_e32 v6, v6
	v_mul_f32_e32 v7, v7, v36
	v_mul_f32_e32 v0, v0, v36
	v_mul_f32_e32 v3, v3, v36
	v_cvt_i32_f32_e32 v5, v4
	v_cvt_i32_f32_e32 v6, v6
	v_rndne_f32_e32 v7, v7
	v_rndne_f32_e32 v0, v0
	v_mul_f32_e32 v1, v1, v36
	v_mul_f32_e32 v2, v2, v36
	v_rndne_f32_e32 v3, v3
	v_med3_i32 v9, v9, -7, 7
	v_med3_i32 v10, v10, -7, 7
	v_cvt_i32_f32_e32 v7, v7
	v_cvt_i32_f32_e32 v0, v0
	v_rndne_f32_e32 v1, v1
	v_rndne_f32_e32 v2, v2
	v_cvt_i32_f32_e32 v3, v3
	v_lshlrev_b32_e32 v9, 20, v9
	v_lshlrev_b32_e32 v10, 24, v10
	v_cvt_i32_f32_e32 v1, v1
	v_cvt_i32_f32_e32 v2, v2
	v_and_b32_e32 v9, 0xf00000, v9
	v_and_b32_e32 v10, 0xf000000, v10
	v_or3_b32 v4, v8, v9, v10
	v_med3_i32 v8, v11, -7, 7
	v_med3_i32 v5, v5, -7, 7
	v_med3_i32 v6, v6, -7, 7
	v_and_b32_e32 v8, 15, v8
	v_lshlrev_b32_e32 v5, 4, v5
	v_lshlrev_b32_e32 v6, 8, v6
	v_med3_i32 v7, v7, -7, 7
	v_med3_i32 v0, v0, -7, 7
	v_med3_i32 v3, v3, -7, 7
	v_and_b32_e32 v5, 0xf0, v5
	v_and_b32_e32 v6, 0xf00, v6
	v_lshlrev_b32_e32 v7, 12, v7
	v_lshlrev_b32_e32 v0, 16, v0
	v_med3_i32 v1, v1, -7, 7
	v_med3_i32 v2, v2, -7, 7
	v_lshl_or_b32 v3, v3, 28, v8
	v_and_b32_e32 v7, 0xf000, v7
	v_and_b32_e32 v0, 0xf0000, v0
	v_lshlrev_b32_e32 v1, 20, v1
	v_lshlrev_b32_e32 v2, 24, v2
	v_or3_b32 v3, v3, v5, v6
	v_and_b32_e32 v1, 0xf00000, v1
	v_and_b32_e32 v2, 0xf000000, v2
	v_or3_b32 v0, v3, v7, v0
	v_or3_b32 v5, v0, v1, v2
	global_store_dwordx2 v[22:23], v[4:5], off
	s_and_saveexec_b64 s[6:7], s[4:5]
	s_cbranch_execz .LBB0_797
	v_add_u32_e32 v0, s0, v17
	v_ashrrev_i32_e32 v1, 31, v0
	v_mul_f32_e32 v2, 0x3e124925, v18
	v_lshl_add_u64 v[0:1], v[0:1], 2, s[12:13]
	global_store_dword v[0:1], v2, off
